# PGATE epilogue: first residual/projection loads issued before the row-scale round trip completes
# speedup vs baseline: 1.0135x; 1.0028x over previous
; #define EP_LOAD(q) do { _Pragma("unroll") for (int bj = 0; bj < 2; ++bj) { const unsigned o = ER_OFF(q, bj); t[(q) & 1][bj] = *(const u32x4*)(base + o); pw[(q) & 1][bj] = *(const u32x4*)(pp + o); } } while (0)
; __device__ __forceinline__ void load_rstd(float (&rsv)[2][4], const ssq_t* ssq, int row0) {
;     ssq_t t[2][4];
; #pragma unroll
;     for (int ai = 0; ai < 2; ++ai)
; #pragma unroll
;         for (int m = 0; m < 4; ++m) t[ai][m] = ssq[row0 + ai * HALF + m * 16];
; #pragma unroll
;     for (int ai = 0; ai < 2; ++ai)
; #pragma unroll
;         for (int m = 0; m < 4; ++m) rsv[ai][m] = __builtin_amdgcn_rsqf((float)t[ai][m] * (SSQ_INV / 1024.0f) + 1e-6f);
;     __device__ __forceinline__ void operator()(f32x4 (&acc)[2][2][4][2], const Unit& u, int wr, int wc, int fr, int fq) const {
;         const int row0 = u.pm * BM + wr * 64 + fr, col0 = u.pn * BM + wc * 32 + 8 * fq; const unsigned off0 = (unsigned)row0 * 1024u + (unsigned)col0;
;         float rsv[2][4]; load_rstd(rsv, ssq, row0);
;         u32x4 t[2][2], pw[2][2];
;     ...
;         bf16_t* hb = pp;
;         EP_LOAD(0); EP_LOAD(1); EP_ADD(0); EP_ADD(1);
.LBB0_238:
	v_mov_b32_e32 v128, v170
	s_lshl_b32 s13, s69, 8
	v_readfirstlane_b32 s12, v128
	s_ashr_i32 s46, s12, 2
	s_andn2_b32 s46, s46, 63
	s_lshr_b32 s12, s12, 1
	s_add_i32 s46, s46, s13
	s_lshl_b32 s13, s68, 8
	s_and_b32 s12, s12, 0x60
	v_bfe_u32 v199, v128, 4, 2
	v_and_or_b32 v192, v128, 15, s46
	s_or_b32 s12, s12, s13
	v_lshl_or_b32 v128, v199, 3, s12
	v_ashrrev_i32_e32 v193, 31, v192
	v_lshl_add_u32 v190, v192, 10, v128
	v_lshl_add_u64 v[128:129], v[192:193], 3, s[26:27]
	global_load_dwordx2 v[130:131], v[128:129], off
	global_load_dwordx2 v[212:213], v[128:129], off offset:128
	global_load_dwordx2 v[202:203], v[128:129], off offset:256
	global_load_dwordx2 v[196:197], v[128:129], off offset:384
	global_load_dwordx2 v[194:195], v[128:129], off offset:1024
	global_load_dwordx2 v[188:189], v[128:129], off offset:1152
	global_load_dwordx2 v[186:187], v[128:129], off offset:1280
	global_load_dwordx2 v[166:167], v[128:129], off offset:1408
	v_mov_b32_e32 v191, v169
	v_add_u32_e32 v168, 0x4000, v190
	v_cmp_eq_u32_e32 vcc, 0, v199
	v_cmp_lt_i32_e64 s[12:13], v233, v228
	v_lshl_add_u64 v[192:193], v[192:193], 3, s[40:41]
	v_lshlrev_b64 v[136:137], 1, v[190:191]
	v_lshl_add_u64 v[138:139], s[70:71], 0, v[136:137]
	global_load_dwordx4 v[152:155], v[138:139], off
	v_lshl_add_u64 v[214:215], s[20:21], 0, v[136:137]
	global_load_dwordx4 v[156:159], v[214:215], off
	global_load_dwordx4 v[144:147], v[138:139], off offset:256
	global_load_dwordx4 v[148:151], v[214:215], off offset:256
	s_waitcnt vmcnt(4)
	v_ffbh_u32_e32 v128, v131
	v_min_u32_e32 v132, 32, v128
	v_lshlrev_b64 v[128:129], v132, v[130:131]
	v_min_u32_e32 v128, 1, v128
	v_or_b32_e32 v128, v129, v128
	v_cvt_f32_u32_e32 v128, v128
	v_sub_u32_e32 v129, 32, v132
	v_ldexp_f32 v128, v128, v129
	v_fmamk_f32 v128, v128, 0x30800000, v223
	v_rsq_f32_e32 v198, v128
	s_nop 1
	v_pk_mul_f32 v[200:201], v[120:121], v[198:199] op_sel_hi:[1,0]
	v_pk_mul_f32 v[120:121], v[126:127], v[198:199] op_sel_hi:[1,0]
	v_mul_f32_e32 v127, 0xbfb8aa3b, v200
	v_exp_f32_e32 v127, v127
	v_pk_mul_f32 v[122:123], v[122:123], v[198:199] op_sel_hi:[1,0]
	v_pk_mul_f32 v[124:125], v[124:125], v[198:199] op_sel_hi:[1,0]
	v_mul_f32_e32 v122, 0xbfb8aa3b, v122
	v_add_f32_e32 v127, 1.0, v127
	v_rcp_f32_e32 v127, v127
	v_exp_f32_e32 v122, v122
	v_mul_f32_e32 v123, 0xbfb8aa3b, v123
	v_exp_f32_e32 v123, v123
	v_mul_f32_e32 v120, 0xbfb8aa3b, v120
	v_add_f32_e32 v122, 1.0, v122
	v_rcp_f32_e32 v122, v122
	v_add_f32_e32 v123, 1.0, v123
	v_rcp_f32_e32 v123, v123
	v_exp_f32_e32 v120, v120
	v_mul_f32_e32 v121, 0xbfb8aa3b, v121
	v_pk_mul_f32 v[116:117], v[116:117], v[198:199] op_sel_hi:[1,0]
	v_exp_f32_e32 v121, v121
	v_mul_f32_e32 v116, 0xbfb8aa3b, v116
	v_exp_f32_e32 v116, v116
	v_mul_f32_e32 v117, 0xbfb8aa3b, v117
	v_exp_f32_e32 v117, v117
	v_add_f32_e32 v120, 1.0, v120
	v_rcp_f32_e32 v120, v120
	v_add_f32_e32 v121, 1.0, v121
	v_rcp_f32_e32 v121, v121
	v_add_f32_e32 v116, 1.0, v116
	v_rcp_f32_e32 v116, v116
	v_add_f32_e32 v117, 1.0, v117
	v_rcp_f32_e32 v117, v117
	v_pk_mul_f32 v[118:119], v[118:119], v[198:199] op_sel_hi:[1,0]
	v_pk_mul_f32 v[112:113], v[112:113], v[198:199] op_sel_hi:[1,0]
	v_pk_mul_f32 v[114:115], v[114:115], v[198:199] op_sel_hi:[1,0]
	v_mul_f32_e32 v112, 0xbfb8aa3b, v112
	v_exp_f32_e32 v112, v112
	v_mul_f32_e32 v113, 0xbfb8aa3b, v113
	v_exp_f32_e32 v113, v113
	v_lshlrev_b64 v[128:129], 1, v[168:169]
	v_add_f32_e32 v112, 1.0, v112
	v_rcp_f32_e32 v112, v112
	v_add_f32_e32 v113, 1.0, v113
	v_rcp_f32_e32 v113, v113
	v_add_u32_e32 v168, 0x4080, v190
	v_lshlrev_b64 v[132:133], 1, v[168:169]
	v_add_u32_e32 v168, 0x8000, v190
	v_lshl_add_u64 v[130:131], s[70:71], 0, v[128:129]
	global_load_dwordx4 v[136:139], v[130:131], off
	v_lshl_add_u64 v[210:211], s[20:21], 0, v[128:129]
	v_lshl_add_u64 v[128:129], s[70:71], 0, v[132:133]
	v_lshl_add_u64 v[206:207], s[20:21], 0, v[132:133]
	global_load_dwordx4 v[140:143], v[210:211], off
	global_load_dwordx4 v[132:135], v[206:207], off
	s_waitcnt vmcnt(5)
	v_lshlrev_b32_e32 v126, 16, v156
	v_lshlrev_b32_e32 v191, 16, v152
	v_fmac_f32_e32 v191, v127, v126
	v_mul_f32_e32 v127, 0xbfb8aa3b, v201
	v_exp_f32_e32 v127, v127
	v_and_b32_e32 v220, 0xffff0000, v152
	v_and_b32_e32 v126, 0xffff0000, v156
	v_lshlrev_b32_e32 v221, 16, v153
	v_add_f32_e32 v127, 1.0, v127
	v_rcp_f32_e32 v127, v127
	v_and_b32_e32 v239, 0xffff0000, v153
	v_lshlrev_b32_e32 v240, 16, v154
	v_and_b32_e32 v241, 0xffff0000, v154
	v_fmac_f32_e32 v220, v127, v126
	v_lshlrev_b32_e32 v126, 16, v157
	v_fmac_f32_e32 v221, v122, v126
	v_and_b32_e32 v122, 0xffff0000, v157
	v_fmac_f32_e32 v239, v123, v122
	v_mul_f32_e32 v123, 0xbfb8aa3b, v124
	v_exp_f32_e32 v123, v123
	v_lshlrev_b32_e32 v122, 16, v158
	v_lshlrev_b32_e32 v242, 16, v155
	v_and_b32_e32 v243, 0xffff0000, v155
	v_add_f32_e32 v123, 1.0, v123
	v_rcp_f32_e32 v123, v123
	s_waitcnt vmcnt(4)
; #define EP_LOAD(q) do { _Pragma("unroll") for (int bj = 0; bj < 2; ++bj) { const unsigned o = ER_OFF(q, bj); t[(q) & 1][bj] = *(const u32x4*)(base + o); pw[(q) & 1][bj] = *(const u32x4*)(pp + o); } } while (0)
;     __device__ __forceinline__ void operator()(f32x4 (&acc)[2][2][4][2], const Unit& u, int wr, int wc, int fr, int fq) const {
;     ...
;         bf16_t* hb = pp;
;         EP_LOAD(0); EP_LOAD(1); EP_ADD(0); EP_ADD(1);
; #pragma unroll
;         for (int q = 0; q < 8; q += 2) { if (q < 6) { EP_LOAD(q + 2); EP_LOAD(q + 3); } ER_STORE(q); ER_STORE(q + 1); if (q < 6) { EP_ADD(q + 2); EP_ADD(q + 3); } }
	v_lshlrev_b32_e32 v226, 16, v144
	v_and_b32_e32 v227, 0xffff0000, v144
	v_lshlrev_b32_e32 v237, 16, v145
	v_fmac_f32_e32 v240, v123, v122
	v_mul_f32_e32 v123, 0xbfb8aa3b, v125
	v_exp_f32_e32 v123, v123
	v_and_b32_e32 v122, 0xffff0000, v158
	v_and_b32_e32 v248, 0xffff0000, v145
	v_lshlrev_b32_e32 v249, 16, v146
	v_add_f32_e32 v123, 1.0, v123
	v_rcp_f32_e32 v123, v123
	v_and_b32_e32 v250, 0xffff0000, v146
	v_lshlrev_b32_e32 v251, 16, v147
	v_and_b32_e32 v252, 0xffff0000, v147
	v_fmac_f32_e32 v241, v123, v122
	v_lshlrev_b32_e32 v122, 16, v159
	v_fmac_f32_e32 v242, v120, v122
	v_and_b32_e32 v120, 0xffff0000, v159
	v_fmac_f32_e32 v243, v121, v120
	s_waitcnt vmcnt(3)
	v_lshlrev_b32_e32 v120, 16, v148
	v_fmac_f32_e32 v226, v116, v120
	v_and_b32_e32 v116, 0xffff0000, v148
	v_fmac_f32_e32 v227, v117, v116
	v_mul_f32_e32 v117, 0xbfb8aa3b, v118
	v_exp_f32_e32 v117, v117
	v_lshlrev_b32_e32 v116, 16, v149
	v_add_f32_e32 v117, 1.0, v117
	v_rcp_f32_e32 v117, v117
	s_nop 0
	v_fmac_f32_e32 v237, v117, v116
	v_mul_f32_e32 v117, 0xbfb8aa3b, v119
	v_exp_f32_e32 v117, v117
	v_and_b32_e32 v116, 0xffff0000, v149
	v_add_f32_e32 v117, 1.0, v117
	v_rcp_f32_e32 v117, v117
	s_nop 0
	v_fmac_f32_e32 v248, v117, v116
	v_lshlrev_b32_e32 v116, 16, v150
	v_fmac_f32_e32 v249, v112, v116
	v_and_b32_e32 v112, 0xffff0000, v150
	v_fmac_f32_e32 v250, v113, v112
	v_mul_f32_e32 v113, 0xbfb8aa3b, v114
	v_exp_f32_e32 v113, v113
	v_lshlrev_b32_e32 v112, 16, v151
	v_add_f32_e32 v113, 1.0, v113
	v_rcp_f32_e32 v113, v113
	s_nop 0
	v_fmac_f32_e32 v251, v113, v112
	v_mul_f32_e32 v113, 0xbfb8aa3b, v115
	v_exp_f32_e32 v113, v113
	v_and_b32_e32 v112, 0xffff0000, v151
	v_add_f32_e32 v113, 1.0, v113
	v_rcp_f32_e32 v113, v113
	s_nop 0
	v_fmac_f32_e32 v252, v113, v112
	v_lshlrev_b64 v[112:113], 1, v[168:169]
	v_add_u32_e32 v168, 0x8080, v190
	v_lshl_add_u64 v[114:115], s[70:71], 0, v[112:113]
	v_lshl_add_u64 v[208:209], s[20:21], 0, v[112:113]
	v_lshlrev_b64 v[112:113], 1, v[168:169]
	v_add_u32_e32 v168, 0xc000, v190
	global_load_dwordx4 v[152:155], v[114:115], off
	v_lshl_add_u64 v[114:115], s[70:71], 0, v[112:113]
	v_lshl_add_u64 v[204:205], s[20:21], 0, v[112:113]
	v_lshlrev_b64 v[112:113], 1, v[168:169]
	v_add_u32_e32 v168, 0xc080, v190
	v_lshl_add_u64 v[200:201], s[20:21], 0, v[112:113]
	v_lshlrev_b64 v[116:117], 1, v[168:169]
	global_load_dwordx4 v[144:147], v[114:115], off
	global_load_dwordx4 v[124:127], v[200:201], off
	v_lshl_add_u64 v[114:115], s[70:71], 0, v[112:113]
	v_lshl_add_u64 v[112:113], s[70:71], 0, v[116:117]
	v_lshl_add_u64 v[198:199], s[20:21], 0, v[116:117]
	global_load_dwordx4 v[128:131], v[128:129], off
	s_nop 0
	global_load_dwordx4 v[156:159], v[208:209], off
	global_load_dwordx4 v[148:151], v[204:205], off
	global_load_dwordx4 v[120:123], v[114:115], off
	global_load_dwordx4 v[116:119], v[198:199], off
	s_nop 0
	global_load_dwordx4 v[112:115], v[112:113], off
	v_cvt_pk_bf16_f32 v244, v191, v220
	v_cvt_pk_bf16_f32 v245, v221, v239
	v_cvt_pk_bf16_f32 v246, v240, v241
	v_cvt_pk_bf16_f32 v247, v242, v243
	global_store_dwordx4 v[214:215], v[244:247], off
	v_and_b32_e32 v191, 0xffff0000, v244
	v_lshlrev_b32_e32 v168, 16, v244
	v_mul_f32_e32 v191, v191, v191
	v_and_b32_e32 v220, 0xffff0000, v245
	v_fmac_f32_e32 v191, v168, v168
	v_lshlrev_b32_e32 v168, 16, v245
	v_mul_f32_e32 v220, v220, v220
	v_fmac_f32_e32 v220, v168, v168
	v_add_f32_e32 v168, v191, v220
	v_and_b32_e32 v220, 0xffff0000, v246
	v_lshlrev_b32_e32 v191, 16, v246
	v_mul_f32_e32 v220, v220, v220
	v_fmac_f32_e32 v220, v191, v191
	v_add_f32_e32 v168, v168, v220
	v_and_b32_e32 v220, 0xffff0000, v247
	v_lshlrev_b32_e32 v191, 16, v247
	v_mul_f32_e32 v220, v220, v220
	v_cvt_pk_bf16_f32 v240, v226, v227
	v_cvt_pk_bf16_f32 v241, v237, v248
	v_cvt_pk_bf16_f32 v242, v249, v250
	v_cvt_pk_bf16_f32 v243, v251, v252
	global_store_dwordx4 v[214:215], v[240:243], off offset:256
	v_and_b32_e32 v214, 0xffff0000, v240
	v_fmac_f32_e32 v220, v191, v191
	v_lshlrev_b32_e32 v191, 16, v240
	v_mul_f32_e32 v214, v214, v214
	v_add_f32_e32 v168, v168, v220
	v_fmac_f32_e32 v214, v191, v191
	v_add_f32_e32 v168, v168, v214
	v_and_b32_e32 v214, 0xffff0000, v241
	v_lshlrev_b32_e32 v191, 16, v241
	v_mul_f32_e32 v214, v214, v214
	v_fmac_f32_e32 v214, v191, v191
	v_add_f32_e32 v168, v168, v214
	v_and_b32_e32 v214, 0xffff0000, v242
	v_lshlrev_b32_e32 v191, 16, v242
	v_mul_f32_e32 v214, v214, v214
	v_fmac_f32_e32 v214, v191, v191
	v_add_f32_e32 v168, v168, v214
	v_and_b32_e32 v214, 0xffff0000, v243
	v_lshlrev_b32_e32 v191, 16, v243
	v_mul_f32_e32 v214, v214, v214
	v_fmac_f32_e32 v214, v191, v191
	v_cndmask_b32_e64 v191, v225, v233, s[12:13]
	v_add_f32_e32 v168, v168, v214
	v_lshlrev_b32_e32 v191, 2, v191
	ds_bpermute_b32 v214, v191, v168
	v_cmp_lt_i32_e64 s[12:13], v234, v228
	s_waitcnt lgkmcnt(0)
	v_add_f32_e32 v168, v168, v214
	v_cndmask_b32_e64 v214, v225, v234, s[12:13]
	v_lshlrev_b32_e32 v214, 2, v214
	ds_bpermute_b32 v215, v214, v168
	s_and_saveexec_b64 s[12:13], vcc
	s_cbranch_execz .LBB0_240
	s_waitcnt lgkmcnt(0)
	v_add_f32_e32 v168, v168, v215
	v_mul_f32_e32 v168, 0x49800000, v168
	v_trunc_f32_e32 v168, v168
	v_mul_f32_e32 v215, 0x2f800000, v168
	v_floor_f32_e32 v215, v215
	v_fmac_f32_e32 v168, 0xcf800000, v215
	v_cvt_u32_f32_e32 v220, v168
	v_cvt_u32_f32_e32 v221, v215
	global_atomic_add_x2 v[192:193], v[220:221], off
